# mix2 loop top: K/V image writes no longer wait for the previous chunk's output stores (short path drains in a stub)
# baseline (speedup 1.0000x reference)
; #define LAS __attribute__((address_space(3)))
; __device__ void mix_sweep(const Params& P, LAS unsigned char* lds, int tok0, int pos0, int seqlen, int hd, int dir, bool state_only, bool final_pass,
;                           f32x4 (&Cacc)[9], float& m_state, float& aseg_sum, float lgam) {
;     ...
;     LAS float* vrow = (LAS float*)(lds + VEC0); LAS float* vcol = vrow + 128; LAS float* vwi = vrow + 256; LAS float* vkw = vrow + 384; LAS float* vemt = vrow + 512; LAS float* vsc = vrow + 640;
;     const int qcol = is_m ? 2048 + h * 128 : h * 128, kcol = is_m ? 2560 + h * 128 : 512 + h * 128, vcolg = is_m ? 3072 + h * 128 : 1024 + h * 128;
;     const int gcol = is_m ? 3584 + h * 128 : 1536 + h * 128, mcol = is_m ? 512 + h * 128 : h * 128;
;     const float* gnw = (is_m ? P.in[11] : P.in[10]) + h * 128;
;     const float LOG2E = 1.4426950408889634f;
;     FragB FB; fragb_init(FB, w, fr, fg);
;     unsigned ktb0, ktb1; { const unsigned q = fr >> 2, p = fr & 3, L = (q << 2) | ((fg & 1u) << 1) | (p >> 1); ktb0 = 256u * (8u * fg + q) + 8u * (p & 1u) + 16u * (L ^ (2u * w)); ktb1 = 256u * (8u * fg + q) + 8u * (p & 1u) + 16u * (L ^ (2u * w + 1u)); asm volatile("" : "+v"(ktb0)); asm volatile("" : "+v"(ktb1)); }
;     __syncthreads();
;     if (!state_only) {
; #pragma unroll
;         for (int nt = 0; nt < 8; ++nt) { u32x2 v; v.x = cvt_pk_bf16(Cacc[nt][0], Cacc[nt][1]); v.y = cvt_pk_bf16(Cacc[nt][2], Cacc[nt][3]);
;             { LAUNDER_X16 *(LAS u32x2*)(lds + IMG_C + CWA(nt)) = v; } }
;         { u32x2 v; v.x = cvt_pk_bf16(Cacc[8][0], Cacc[8][1]); v.y = cvt_pk_bf16(Cacc[8][2], Cacc[8][3]); *(LAS u32x2*)(lds + IMG_CX + 32 * (16 * w + fr) + 8 * fg) = v; }
;     }
;     if (tid < 128) { unsigned zz = 0u; asm volatile("" : "+v"(zz)); u32x4 v0 = (u32x4){is_m ? 0x3F80u : zz, zz, zz, zz}; u32x4 z = (u32x4){zz, zz, zz, zz}; *(LAS u32x4*)(lds + IMG_VX + 32 * tid) = v0; *(LAS u32x4*)(lds + IMG_VX + 32 * tid + 16) = z; }
;     LAS float* PV = (LAS float*)(lds + 141888); LAS float* PS = PV + 8 * 3 * 128;
;     if (is_m) { const int c = dir ? 7 - w : w; const int tokc = tok0 + c * 128;
;         const int u0 = 2 * lane, u1 = 2 * lane + 1; const int j0 = dir ? 127 - u0 : u0, j1 = dir ? 127 - u1 : u1;
;         const float x0 = gates[(size_t)(tokc + j0) * 16 + 8 + dir * 4 + h], x1 = gates[(size_t)(tokc + j1) * 16 + 8 + dir * 4 + h];
.LBB0_96:
	s_and_b64 s[14:15], s[8:9], exec
	v_and_b32_e32 v0, 0x78, v0
	s_cselect_b32 s14, 0, 0x380
	v_lshlrev_b32_e32 v0, 1, v0
	s_or_b32 s14, s14, s79
	s_waitcnt lgkmcnt(2)
	v_lshl_add_u64 v[2:3], s[22:23], 0, v[0:1]
	v_ashrrev_i32_e32 v0, 4, v161
	v_add_u32_e32 v40, s14, v0
	v_add_u32_e32 v0, 0x200, v161
	v_ashrrev_i32_e32 v0, 4, v0
	v_add_u32_e32 v42, s14, v0
	v_add_u32_e32 v0, 0x400, v161
	v_ashrrev_i32_e32 v0, 4, v0
	v_add_u32_e32 v50, s14, v0
	v_add_u32_e32 v0, 0x600, v161
	v_ashrrev_i32_e32 v0, 4, v0
	v_add_u32_e32 v52, s14, v0
	v_ashrrev_i32_e32 v41, 31, v40
	s_lshl_b32 s38, s80, 1
	v_ashrrev_i32_e32 v43, 31, v42
	v_ashrrev_i32_e32 v51, 31, v50
	v_ashrrev_i32_e32 v53, 31, v52
	s_lshl_b32 s14, s81, 1
	s_mov_b32 s15, s39
	v_lshlrev_b64 v[56:57], 13, v[40:41]
	v_lshl_add_u64 v[48:49], v[2:3], 0, s[38:39]
	v_lshlrev_b64 v[58:59], 13, v[42:43]
	v_lshlrev_b64 v[64:65], 13, v[50:51]
	v_lshlrev_b64 v[66:67], 13, v[52:53]
	v_lshl_add_u64 v[2:3], v[2:3], 0, s[14:15]
	v_lshl_add_u64 v[40:41], v[48:49], 0, v[56:57]
	v_lshl_add_u64 v[44:45], v[48:49], 0, v[58:59]
	v_lshl_add_u64 v[50:51], v[48:49], 0, v[64:65]
	v_lshl_add_u64 v[52:53], v[48:49], 0, v[66:67]
	v_lshl_add_u64 v[56:57], v[2:3], 0, v[56:57]
	v_lshl_add_u64 v[60:61], v[2:3], 0, v[58:59]
	v_lshl_add_u64 v[64:65], v[2:3], 0, v[64:65]
	global_load_dwordx4 v[40:43], v[40:41], off
	s_nop 0
	global_load_dwordx4 v[44:47], v[44:45], off
	s_nop 0
	global_load_dwordx4 v[48:51], v[50:51], off
	s_nop 0
	global_load_dwordx4 v[52:55], v[52:53], off
	s_nop 0
	global_load_dwordx4 v[56:59], v[56:57], off
	s_nop 0
	global_load_dwordx4 v[60:63], v[60:61], off
	v_lshl_add_u64 v[2:3], v[2:3], 0, v[66:67]
	global_load_dwordx4 v[64:67], v[64:65], off
	s_nop 0
	global_load_dwordx4 v[68:71], v[2:3], off
	v_lshlrev_b32_e32 v79, 2, v161
	s_add_i32 s15, 0, 0x22000
	v_add_u32_e32 v182, s15, v79
	s_add_i32 s15, 0, 0x22200
	v_lshlrev_b32_e32 v0, 4, v73
	v_add_u32_e32 v183, s15, v79
	v_add_u32_e32 v190, s15, v0
	v_readlane_b32 s15, v253, 49
	s_add_i32 s19, 0, 0x22400
	v_add_u32_e32 v184, s19, v79
	v_add_u32_e32 v194, s15, v75
	s_add_i32 s15, 0, 0x1a000
	v_add_u32_e32 v195, s15, v75
	v_readlane_b32 s15, v253, 50
	s_add_i32 s19, 0, 0x22600
	s_add_i32 s46, 0, 0x22800
	v_add_u32_e32 v196, s15, v75
	s_add_i32 s15, 0, 0x1c000
	v_add_u32_e32 v197, s15, v75
	v_readlane_b32 s15, v253, 51
	v_lshlrev_b32_e32 v189, 2, v73
	v_mov_b32_e32 v73, v1
	v_add_u32_e32 v198, s15, v75
	s_add_i32 s15, 0, 0x1e000
	v_add_u32_e32 v199, s15, v75
	v_readlane_b32 s15, v253, 52
	s_add_i32 s85, 0, 0x10000
	s_mov_b32 s7, 0
	v_add_u32_e32 v200, s15, v75
	v_readlane_b32 s15, v253, 53
	s_mov_b32 s83, 1
	v_add_u32_e32 v185, s19, v79
	v_add_u32_e32 v247, s15, v75
	s_add_i32 s15, 0, 0x12000
	v_add_u32_e32 v248, s15, v75
	v_readlane_b32 s15, v253, 54
	v_add_u32_e32 v187, s46, v79
	v_cmp_eq_u32_e64 s[46:47], 0, v161
	v_add_u32_e32 v249, s15, v75
	s_add_i32 s15, 0, 0x14000
	v_add_u32_e32 v250, s15, v75
	v_readlane_b32 s15, v253, 55
	v_lshl_or_b32 v219, s16, 4, v169
	s_add_i32 s84, s17, 0
	v_add_u32_e32 v251, s15, v75
	s_add_i32 s15, 0, 0x16000
	v_add_u32_e32 v252, s15, v75
	v_readlane_b32 s15, v253, 56
	v_add_u32_e32 v191, 0, v78
	v_lshl_add_u32 v192, v72, 2, s19
	v_lshl_add_u64 v[2:3], s[2:3], 0, v[72:73]
	v_lshl_add_u64 v[152:153], s[4:5], 0, v[72:73]
	v_lshl_add_u64 v[154:155], s[94:95], 0, v[0:1]
	v_add_u32_e32 v193, s18, v75
	v_or_b32_e32 v201, 2, v189
	v_or_b32_e32 v202, 3, v189
	v_or_b32_e32 v204, 16, v189
	v_or_b32_e32 v205, 17, v189
	v_or_b32_e32 v206, 18, v189
	v_or_b32_e32 v207, 19, v189
	v_or_b32_e32 v222, 32, v189
	v_or_b32_e32 v223, 33, v189
	v_or_b32_e32 v224, 34, v189
	v_or_b32_e32 v225, 35, v189
	v_or_b32_e32 v226, 48, v189
	v_or_b32_e32 v227, 49, v189
	v_or_b32_e32 v228, 50, v189
	v_or_b32_e32 v229, 51, v189
	v_or_b32_e32 v230, 64, v189
	v_or_b32_e32 v231, 0x41, v189
	v_or_b32_e32 v232, 0x42, v189
	v_or_b32_e32 v233, 0x43, v189
	v_or_b32_e32 v234, 0x50, v189
	v_or_b32_e32 v235, 0x51, v189
	v_or_b32_e32 v236, 0x52, v189
	v_or_b32_e32 v237, 0x53, v189
	v_or_b32_e32 v238, 0x60, v189
	v_or_b32_e32 v239, 0x61, v189
	v_or_b32_e32 v240, 0x62, v189
	v_or_b32_e32 v241, 0x63, v189
	v_or_b32_e32 v242, 0x70, v189
	v_or_b32_e32 v243, 0x71, v189
	v_or_b32_e32 v244, 0x72, v189
	v_or_b32_e32 v245, 0x73, v189
	v_add_u32_e32 v246, s85, v75
	v_add_u32_e32 v211, s15, v75
	v_add_u32_e32 v164, 0, v79
	s_mov_b32 s86, 6
	s_movk_i32 s87, 0xd000
	v_add_u32_e32 v165, 0, v76
	v_add_u32_e32 v166, 0, v77
	v_add_u32_e32 v167, 0, v74
	v_readlane_b32 s88, v253, 57
	v_lshrrev_b32_e32 v80, 6, v161
	v_lshlrev_b32_e32 v80, 6, v80
	v_mov_b32_e32 v81, 0
	v_lshl_add_u64 v[82:83], v[154:155], 0, v[80:81]
	global_load_dwordx4 v[84:87], v[82:83], off
	v_bfe_u32 v81, v161, 4, 2
	v_lshl_add_u32 v80, v81, 4, v80
	v_add_u32_e32 v80, 0x25a80, v80
	s_waitcnt vmcnt(0)
	ds_write_b128 v80, v[84:87]
	s_branch .LBB0_98
.Lkvw_stub:
	s_waitcnt vmcnt(0)
; #define LAS __attribute__((address_space(3)))
; __device__ __forceinline__ unsigned cvt_pk_bf16(float lo, float hi) { unsigned r; asm volatile("v_cvt_pk_bf16_f32 %0, %1, %2" : "=v"(r) : "v"(lo), "v"(hi)); return r; }
; __device__ void mix_sweep(const Params& P, LAS unsigned char* lds, int tok0, int pos0, int seqlen, int hd, int dir, bool state_only, bool final_pass,
;                           f32x4 (&Cacc)[9], float& m_state, float& aseg_sum, float lgam) {
;     ...
;         const int c = dir ? 7 - ci : ci; const int tok = tok0 + c * 128;
;         __syncthreads();
;         int tl = tid; asm volatile("" : "+v"(tl));
;         if (!state_only) {
; #pragma unroll
;             for (int it = 0; it < 4; ++it) { const int item = tl + 512 * it, r = item >> 4, ch = item & 15; t[0][it] = *(const u32x4*)(proj + (size_t)(tok + r) * NPROJ + qcol + 8 * ch); } }
; #pragma unroll
;     ...
; #pragma unroll
;             for (int it = 0; it < 4; ++it) { const int item = tl + 512 * it, r = item >> 4, ch = item & 15; *(LAS u32x4*)(img + offb(r, ch)) = t[which][it]; } }
;         if (ci < 7) { const int cn = dir ? 6 - ci : ci + 1; const int tokn = tok0 + cn * 128;
; #pragma unroll
;             for (int which = 1; which < 3; ++which) { const int cb = which == 1 ? kcol : vcolg;
; #pragma unroll
;                 for (int it = 0; it < 4; ++it) { const int item = tl + 512 * it, r = item >> 4, ch = item & 15; t[which][it] = *(const u32x4*)(proj + (size_t)(tokn + r) * NPROJ + cb + 8 * ch); } } }
;     ...
;         if (!state_only) {
;             __syncthreads();
; #pragma unroll
;             for (int nt = 0; nt < 8; ++nt) { u32x2 v; v.x = cvt_pk_bf16(Cacc[nt][0], Cacc[nt][1]); v.y = cvt_pk_bf16(Cacc[nt][2], Cacc[nt][3]);
;                 { LAUNDER_X16 *(LAS u32x2*)(lds + IMG_C + CWA(nt)) = v; } }
;             { u32x2 v; v.x = cvt_pk_bf16(Cacc[8][0], Cacc[8][1]); v.y = cvt_pk_bf16(Cacc[8][2], Cacc[8][3]); *(LAS u32x2*)(lds + IMG_CX + 32 * (16 * w + fr) + 8 * fg) = v; }
.LBB0_97:
	v_mov_b32_e32 v0, v179
	s_barrier
	v_cvt_pk_bf16_f32 v72, v32, v33
	v_cvt_pk_bf16_f32 v73, v34, v35
	s_add_i32 s86, s86, -1
	v_add_u32_e32 v0, v180, v0
	ds_write_b64 v0, v[72:73]
	v_mov_b32_e32 v0, v179
	v_cvt_pk_bf16_f32 v72, v28, v29
	v_cvt_pk_bf16_f32 v73, v30, v31
	s_add_i32 s83, s83, 1
	v_xad_u32 v0, v0, 32, v180
	ds_write_b64 v0, v[72:73]
	v_mov_b32_e32 v0, v179
	v_cvt_pk_bf16_f32 v72, v24, v25
	v_cvt_pk_bf16_f32 v73, v26, v27
	s_addk_i32 s87, 0x600
	v_xad_u32 v0, v0, 64, v180
	ds_write_b64 v0, v[72:73]
	v_mov_b32_e32 v0, v179
	v_cvt_pk_bf16_f32 v72, v20, v21
	v_cvt_pk_bf16_f32 v73, v22, v23
	s_add_i32 s88, s88, 8
	v_xad_u32 v0, v0, s33, v180
	ds_write_b64 v0, v[72:73]
	v_mov_b32_e32 v0, v179
	v_cvt_pk_bf16_f32 v72, v16, v17
	v_cvt_pk_bf16_f32 v73, v18, v19
	s_addk_i32 s7, 0x80
	v_xad_u32 v0, v0, s25, v180
	ds_write_b64 v0, v[72:73]
	v_mov_b32_e32 v0, v179
	v_cvt_pk_bf16_f32 v72, v12, v13
	v_cvt_pk_bf16_f32 v73, v14, v15
	s_cmp_lg_u32 s87, 0
	v_xad_u32 v0, v0, s31, v180
	ds_write_b64 v0, v[72:73]
	v_mov_b32_e32 v0, v179
	v_cvt_pk_bf16_f32 v72, v8, v9
	v_cvt_pk_bf16_f32 v73, v10, v11
	s_nop 0
	v_xad_u32 v0, v0, s27, v180
	ds_write_b64 v0, v[72:73]
	v_mov_b32_e32 v0, v179
	v_cvt_pk_bf16_f32 v72, v4, v5
	v_cvt_pk_bf16_f32 v73, v6, v7
	s_nop 0
	v_xad_u32 v0, v0, s97, v180
	ds_write_b64 v0, v[72:73]
	v_cvt_pk_bf16_f32 v72, v36, v37
	v_cvt_pk_bf16_f32 v73, v38, v39
	ds_write_b64 v181, v[72:73]
	s_cbranch_scc0 .LBB0_74
.LBB0_98:
	s_xor_b32 s15, s7, 0x380
	s_and_b64 s[16:17], s[8:9], exec
	s_cselect_b32 s89, s7, s15
	v_mov_b32_e32 v92, v161
	s_add_i32 s89, s89, s79
	s_waitcnt lgkmcnt(0)
	s_barrier
	s_cmpk_eq_i32 s87, 0xfa00
	v_lshlrev_b32_e32 v0, 3, v92
	v_ashrrev_i32_e32 v72, 4, v92
	v_and_b32_e32 v0, 0x78, v0
	v_add_u32_e32 v74, s89, v72
	v_lshlrev_b32_e32 v0, 1, v0
	v_ashrrev_i32_e32 v75, 31, v74
	v_lshl_add_u64 v[88:89], s[36:37], 0, v[0:1]
	v_lshlrev_b64 v[74:75], 13, v[74:75]
	v_add_u32_e32 v73, 0x200, v92
	v_lshl_add_u64 v[74:75], v[88:89], 0, v[74:75]
	v_ashrrev_i32_e32 v73, 4, v73
	global_load_dwordx4 v[76:79], v[74:75], off
	v_add_u32_e32 v74, s89, v73
	v_ashrrev_i32_e32 v75, 31, v74
	v_lshlrev_b64 v[74:75], 13, v[74:75]
	v_lshl_add_u64 v[74:75], v[88:89], 0, v[74:75]
	global_load_dwordx4 v[80:83], v[74:75], off
	v_add_u32_e32 v74, 0x400, v92
	v_ashrrev_i32_e32 v74, 4, v74
	v_add_u32_e32 v75, 0x600, v92
	v_add_u32_e32 v84, s89, v74
	v_ashrrev_i32_e32 v75, 4, v75
	v_ashrrev_i32_e32 v85, 31, v84
	v_add_u32_e32 v90, s89, v75
	v_lshlrev_b64 v[84:85], 13, v[84:85]
	v_ashrrev_i32_e32 v91, 31, v90
	v_lshl_add_u64 v[84:85], v[88:89], 0, v[84:85]
	v_lshlrev_b64 v[90:91], 13, v[90:91]
	global_load_dwordx4 v[84:87], v[84:85], off
	v_lshl_add_u64 v[88:89], v[88:89], 0, v[90:91]
	global_load_dwordx4 v[88:91], v[88:89], off
	v_lshlrev_b32_e32 v94, 2, v72
	v_and_b32_e32 v92, 15, v92
	v_and_b32_e32 v94, 12, v94
	v_bfe_u32 v95, v72, 2, 2
	v_bitop3_b32 v94, v94, v92, v95 bitop3:0x36
	v_lshlrev_b32_e32 v96, 2, v73
	v_lshlrev_b32_e32 v93, 8, v72
	v_lshlrev_b32_e32 v94, 4, v94
	v_and_b32_e32 v96, 12, v96
	v_bfe_u32 v97, v73, 2, 2
	v_add3_u32 v95, s85, v94, v93
	v_bitop3_b32 v96, v96, v92, v97 bitop3:0x36
	v_lshlrev_b32_e32 v98, 2, v74
	ds_write_b128 v95, v[56:59]
	v_lshlrev_b32_e32 v95, 8, v73
	v_lshlrev_b32_e32 v96, 4, v96
	v_and_b32_e32 v98, 12, v98
	v_bfe_u32 v99, v74, 2, 2
	v_add3_u32 v97, s85, v96, v95
	v_bitop3_b32 v98, v98, v92, v99 bitop3:0x36
	v_lshlrev_b32_e32 v100, 2, v75
	ds_write_b128 v97, v[60:63]
	v_lshlrev_b32_e32 v97, 8, v74
	v_lshlrev_b32_e32 v98, 4, v98
	v_and_b32_e32 v100, 12, v100
	v_bfe_u32 v101, v75, 2, 2
	v_add3_u32 v99, s85, v98, v97
	v_bitop3_b32 v92, v100, v92, v101 bitop3:0x36
	ds_write_b128 v99, v[64:67]
	v_lshlrev_b32_e32 v99, 8, v75
	v_lshlrev_b32_e32 v92, 4, v92
	v_add3_u32 v100, s85, v92, v99
	v_add3_u32 v93, 0, v94, v93
	v_add3_u32 v94, 0, v96, v95
	v_add3_u32 v95, 0, v98, v97
	v_add3_u32 v92, 0, v92, v99
	ds_write_b128 v100, v[68:71]
	ds_write_b128 v93, v[40:43] offset:32768
	ds_write_b128 v94, v[44:47] offset:32768
	ds_write_b128 v95, v[48:51] offset:32768
	ds_write_b128 v92, v[52:55] offset:32768
	s_waitcnt vmcnt(3)
	ds_write_b128 v93, v[76:79]
	s_waitcnt vmcnt(2)
	ds_write_b128 v94, v[80:83]
	s_waitcnt vmcnt(1)
	ds_write_b128 v95, v[84:87]
	s_waitcnt vmcnt(0)
	ds_write_b128 v92, v[88:91]
	s_cbranch_scc1 .LBB0_100
	s_and_b64 s[16:17], s[8:9], exec
	s_cselect_b32 s15, s83, s86
	s_lshl_b32 s15, s15, 7
	s_add_i32 s15, s15, s79
	v_add_u32_e32 v40, s15, v72
	v_add_u32_e32 v42, s15, v73
	v_add_u32_e32 v50, s15, v74
	v_add_u32_e32 v52, s15, v75
	v_lshl_add_u64 v[56:57], s[22:23], 0, v[0:1]
	v_ashrrev_i32_e32 v41, 31, v40
	v_ashrrev_i32_e32 v43, 31, v42
	v_ashrrev_i32_e32 v51, 31, v50
	v_ashrrev_i32_e32 v53, 31, v52
	s_mov_b32 s15, s39
	v_lshlrev_b64 v[58:59], 13, v[40:41]
	v_lshl_add_u64 v[48:49], v[56:57], 0, s[38:39]
	v_lshlrev_b64 v[60:61], 13, v[42:43]
	v_lshlrev_b64 v[64:65], 13, v[50:51]
	v_lshlrev_b64 v[66:67], 13, v[52:53]
	v_lshl_add_u64 v[68:69], v[56:57], 0, s[14:15]
	v_lshl_add_u64 v[40:41], v[48:49], 0, v[58:59]
	v_lshl_add_u64 v[44:45], v[48:49], 0, v[60:61]
	v_lshl_add_u64 v[50:51], v[48:49], 0, v[64:65]
	v_lshl_add_u64 v[52:53], v[48:49], 0, v[66:67]
	v_lshl_add_u64 v[56:57], v[68:69], 0, v[58:59]
	v_lshl_add_u64 v[60:61], v[68:69], 0, v[60:61]
	v_lshl_add_u64 v[64:65], v[68:69], 0, v[64:65]
	v_lshl_add_u64 v[68:69], v[68:69], 0, v[66:67]
	global_load_dwordx4 v[40:43], v[40:41], off
	s_nop 0
	global_load_dwordx4 v[44:47], v[44:45], off
	s_nop 0
	global_load_dwordx4 v[48:51], v[50:51], off
	s_nop 0
	global_load_dwordx4 v[52:55], v[52:53], off
	s_nop 0
	global_load_dwordx4 v[56:59], v[56:57], off
	s_nop 0
	global_load_dwordx4 v[60:63], v[60:61], off
	s_nop 0
	global_load_dwordx4 v[64:67], v[64:65], off
	s_nop 0
	global_load_dwordx4 v[68:71], v[68:69], off
